# work-queue pop: the fetch-add is issued without first draining the previous item's stores (its round trip overlaps their acknowledgement)
# speedup vs baseline: 1.0061x; 1.0006x over previous
.LBB0_327:
	s_barrier
	s_and_saveexec_b64 s[8:9], s[6:7]
	s_cbranch_execz .LBB0_331
	s_mov_b64 s[12:13], exec
	v_mbcnt_lo_u32_b32 v0, s12, 0
	v_mbcnt_hi_u32_b32 v0, s13, v0
	v_cmp_eq_u32_e32 vcc, 0, v0
	s_and_saveexec_b64 s[10:11], vcc
	s_cbranch_execz .LBB0_330
	s_bcnt1_i32_b64 s3, s[12:13]
	s_nop 0
	v_mov_b32_e32 v2, s3
	global_atomic_add v2, v1, v2, s[26:27] sc0
